# phase 2: the 32 gate columns computed before the main GEMM tiles (h still cache-resident after phase 1) instead of after
# baseline (speedup 1.0000x reference)
; #define MFMA32(a, b, c) __builtin_amdgcn_mfma_f32_32x32x16_bf16((a), (b), (c), 0, 0, 0)
; DI int crow(int reg, int hh) { return (reg & 3) + 8 * (reg >> 2) + 4 * hh; }
; #define PH(n) if (p.ph_lo <= (n) && (n) < p.ph_hi) { run_phase<n>(p, smem); \
;         if ((REPEAT_MASK >> (n)) & 1) { SEAM(n); run_phase<n>(p, smem); } \
;         if ((n) + 1 < p.ph_hi) SEAM(n); }
; DI void gates_gemm(const Params& p) {
;     const int wave = threadIdx.x >> 6, lane = threadIdx.x & 63, r = lane & 31, hh = lane >> 5;
;     const int gw = blockIdx.x * 8 + wave, NGW = gridDim.x * 8;
;     const bf16_t* H = (const bf16_t*)(p.ws + OFF_A); const bf16_t* WG = (const bf16_t*)(p.ws + OFF_WG);
;     float* graw = (float*)(p.ws + OFF_GRAW);
;     for (int rg = gw; rg < MTOT / 32; rg += NGW) {
;         f32x16 acc; for (int i = 0; i < 16; ++i) acc[i] = 0.f;
;         const bf16_t* ap = H + (size_t)(32 * rg + r) * DM + 8 * hh; const bf16_t* bp = WG + (size_t)r * DM + 8 * hh;
; #pragma unroll 8
;         for (int s = 0; s < 64; ++s) { const bf16x8 a = *(const bf16x8*)(ap + 16 * s), b = *(const bf16x8*)(bp + 16 * s); acc = MFMA32(a, b, acc); }
; #pragma unroll
;         for (int i = 0; i < 16; ++i) graw[(size_t)(32 * rg + crow(i, hh)) * 32 + r] = acc[i];
;     }
; template <int PH>
; DI void run_phase(const Params& p, unsigned char* smem) {
;     ...
;     if constexpr (PH == 2) { pg8::Gemm g{(const bf16_t*)(p.ws + OFF_A), (const bf16_t*)(p.ws + OFF_WIN), MTOT, 4096, 1024};
;                   pg8::StaticOrder S; S.init(g.M, g.N, gridDim.x, blockIdx.x);
;                   pg8::EpiBf16 E{(bf16_t*)(p.ws + OFF_P), (bf16_t*)(p.ws + OFF_P) + (size_t)MTOT * P1W};
;                   pg8::gemm_phase(lds, g, S, E);
;                   gates_gemm(p); }
.LBB0_203:
	s_cmp_lt_i32 s68, 3
	s_cselect_b64 s[4:5], -1, 0
	s_cmp_gt_i32 s69, 2
	s_cselect_b64 s[6:7], -1, 0
	s_and_b64 s[4:5], s[4:5], s[6:7]
	s_andn2_b64 vcc, exec, s[4:5]
	s_cbranch_vccnz .LBB0_275
	s_waitcnt lgkmcnt(0)
	s_load_dword s3, s[0:1], 0xb8
	s_waitcnt lgkmcnt(0)
	s_mov_b64 s[4:5], exec
	v_and_b32_e32 v0, 63, v180
	v_and_b32_e32 v1, 31, v0
	v_lshrrev_b32_e32 v2, 5, v0
	v_readfirstlane_b32 s70, v181
	s_lshl_b32 s71, s70, 8
	s_add_u32 s72, s30, 0x2376000
	s_addc_u32 s73, s31, 0
	s_add_u32 s72, s72, s71
	s_addc_u32 s73, s73, 0
	s_add_u32 s84, s30, 0x800000
	s_addc_u32 s85, s31, 0
	s_add_u32 s84, s84, s71
	s_addc_u32 s85, s85, 0
	s_add_u32 s80, s30, 0x1af6000
	s_addc_u32 s81, s31, 0
	s_lshl_b32 s78, s70, 13
	s_mov_b32 s76, s2
	v_lshlrev_b32_e32 v4, 11, v1
	v_lshl_add_u32 v4, v2, 4, v4
	global_load_dwordx4 v[8:11], v4, s[84:85]
	global_load_dwordx4 v[12:15], v4, s[84:85] offset:32
	global_load_dwordx4 v[16:19], v4, s[84:85] offset:64
	global_load_dwordx4 v[20:23], v4, s[84:85] offset:96
	global_load_dwordx4 v[24:27], v4, s[84:85] offset:128
	global_load_dwordx4 v[28:31], v4, s[84:85] offset:160
	global_load_dwordx4 v[32:35], v4, s[84:85] offset:192
	global_load_dwordx4 v[36:39], v4, s[84:85] offset:224
	v_lshrrev_b32_e32 v5, 3, v0
	v_lshrrev_b32_e32 v6, 4, v0
	v_and_b32_e32 v40, 7, v0
	v_xor_b32_e32 v40, v40, v6
	v_lshlrev_b32_e32 v40, 4, v40
	v_lshl_add_u32 v40, v5, 11, v40
	v_xor_b32_e32 v41, 64, v40
	v_bfe_u32 v6, v1, 1, 3
	v_xor_b32_e32 v6, v6, v2
	v_lshlrev_b32_e32 v6, 4, v6
	v_lshlrev_b32_e32 v5, 7, v1
	v_add_u32_e32 v5, s78, v5
	v_add_u32_e32 v42, v5, v6
	v_xor_b32_e32 v49, 32, v6
	v_add_u32_e32 v43, v5, v49
	v_xor_b32_e32 v49, 64, v6
	v_add_u32_e32 v44, v5, v49
	v_xor_b32_e32 v49, 96, v6
	v_add_u32_e32 v45, v5, v49
	v_lshlrev_b32_e32 v46, 2, v1
	v_lshl_add_u32 v46, v2, 9, v46
	s_lshl_b32 s79, s70, 12
	s_add_u32 s79, s79, 0x10000
	v_add_u32_e32 v46, s79, v46
	v_lshlrev_b32_e32 v48, 3, v180
	v_add_u32_e32 v47, 0x10000, v48
	s_cmp_lt_u32 s76, 0x880
	s_cbranch_scc0 .Lg2_done
	s_lshl_b32 s86, s76, 16
	s_add_u32 s82, s72, s86
	s_addc_u32 s83, s73, 0
	s_add_i32 m0, s78, 0
	s_add_u32 s74, s82, 0
	s_addc_u32 s75, s83, 0
	global_load_lds_dwordx4 v40, s[74:75]
	s_add_i32 m0, m0, 0x400
	s_add_u32 s74, s74, 0x4000
	s_addc_u32 s75, s75, 0
	global_load_lds_dwordx4 v41, s[74:75]
	s_add_i32 m0, m0, 0x400
	s_add_u32 s74, s74, 0x4000
	s_addc_u32 s75, s75, 0
	global_load_lds_dwordx4 v40, s[74:75]
	s_add_i32 m0, m0, 0x400
	s_add_u32 s74, s74, 0x4000
	s_addc_u32 s75, s75, 0
	global_load_lds_dwordx4 v41, s[74:75]
	s_add_i32 m0, s78, 4096
	s_add_u32 s74, s82, 128
	s_addc_u32 s75, s83, 0
	global_load_lds_dwordx4 v40, s[74:75]
	s_add_i32 m0, m0, 0x400
	s_add_u32 s74, s74, 0x4000
	s_addc_u32 s75, s75, 0
	global_load_lds_dwordx4 v41, s[74:75]
	s_add_i32 m0, m0, 0x400
	s_add_u32 s74, s74, 0x4000
	s_addc_u32 s75, s75, 0
	global_load_lds_dwordx4 v40, s[74:75]
	s_add_i32 m0, m0, 0x400
	s_add_u32 s74, s74, 0x4000
	s_addc_u32 s75, s75, 0
	global_load_lds_dwordx4 v41, s[74:75]

; #define PG8_WAIT_V(n) asm volatile("s_waitcnt vmcnt(" #n ")" ::: "memory")
; #define PG8_BAR __builtin_amdgcn_s_barrier()
;     DI bool next(int i, Unit& u) const {
;     ...
;         int wgid = (int)L; { const int q = nwg / NXCD, r = nwg % NXCD, xcd = wgid % NXCD, off = wgid / NXCD; wgid = (xcd < r ? xcd * (q + 1) : r * (q + 1) + (xcd - r) * q) + off; }
;         const int nig = WGM * nN, gid = wgid / nig, fm = gid * WGM, gsz = (nM - fm) < WGM ? (nM - fm) : WGM;
;         u.pm = fm + ((wgid % nig) % gsz); u.pn = (wgid % nig) / gsz; return true;
; template <class Epi>
; DI void gemm_phase(LAS unsigned char* lds, const Gemm g, const StaticOrder& S, const Epi& E) {
;     const int tid = threadIdx.x, wid = __builtin_amdgcn_readfirstlane(tid >> 6), lane = tid & 63, wr = wid >> 2, wc = wid & 3, fr = lane & 15, fq = lane >> 4;
;     const int K = g.K, nt = K / BK;
;     unsigned voffA[2], voffB[2];
; #pragma unroll
;     for (int i = 0; i < 2; ++i) { int R, C; stage_rc(tid * 16 + i * 8192, R, C); const int Rb = Epi::PERM ? ((R & ~31) + perm32(R & 31)) : R;
;         voffA[i] = (unsigned)(R * K + C) * 2u; voffB[i] = (unsigned)(Rb * K + C) * 2u; }
;     const size_t kstep = (size_t)(BK * 2);
;     const size_t hstep = (size_t)HALF * K * 2;
;     const size_t tstep = 2 * hstep;
;     const unsigned ldsw = (unsigned)wid * 1024u;
;     const int aoff = lds_byte(wr * 64 + fr, fq * 8), boff = lds_byte(wc * 32 + fr, fq * 8);
;     ...
;     Unit cur, nxt; int ui = 0;
;     if (!S.next(0, cur)) return;
;     f32x4 acc[2][2][4][2];
; #pragma unroll
;     for (int a = 0; a < 2; ++a)
; #pragma unroll
;         for (int b = 0; b < 2; ++b)
; #pragma unroll
;             for (int m = 0; m < 4; ++m)
; #pragma unroll
;                 for (int n = 0; n < 2; ++n) acc[a][b][m][n] = (f32x4){0.f, 0.f, 0.f, 0.f};
;     bf16x8 At[4][2], B0[2][2], B1[2][2];
;     const char* cA = (const char*)g.A + (size_t)cur.pm * tstep; const char* cB = (const char*)g.Bt + (size_t)cur.pn * tstep;
;     PG8_STAGE(PG8_SB(0, 0), cB, voffB); PG8_STAGE(PG8_SA(0, 0), cA, voffA); PG8_STAGE(PG8_SB(0, 1), cB + hstep, voffB); PG8_STAGE(PG8_SA(0, 1), cA + hstep, voffA);
;     if (wr == 1) PG8_BAR;
;     PG8_WAIT_V(4); PG8_BAR;
;     PG8_STAGE(PG8_SB(1, 0), cB + kstep, voffB); PG8_STAGE(PG8_SA(1, 0), cA + kstep, voffA); PG8_STAGE(PG8_SB(1, 1), cB + hstep + kstep, voffB);
.Lg2_done:
	s_or_b64 exec, exec, s[4:5]
	s_waitcnt vmcnt(0) lgkmcnt(0)
	s_barrier
	s_add_u32 s6, s0, 0xb8
	s_addc_u32 s7, s1, 0
	s_cmpk_gt_i32 s2, 0x10ff
	v_readfirstlane_b32 s42, v180
	s_cbranch_scc1 .LBB0_216
	v_lshrrev_b32_e32 v0, 5, v180
	v_lshrrev_b32_e32 v2, 1, v180
	v_and_b32_e32 v0, 4, v0
	v_bfe_u32 v1, v180, 2, 2
	v_and_b32_e32 v11, 24, v2
	v_or3_b32 v0, v0, v1, v11
	v_lshlrev_b32_e32 v1, 4, v180
	v_add_u32_e32 v8, 0x2000, v1
	v_lshrrev_b32_e32 v2, 7, v8
	s_movk_i32 s4, 0xe0
	v_and_b32_e32 v4, 32, v180
	v_and_or_b32 v3, v2, s4, v0
	v_bitop3_b32 v9, v1, v4, 48 bitop3:0x6c
	v_and_b32_e32 v10, 64, v180
	v_bfe_u32 v12, v180, 2, 4
	s_movk_i32 s4, 0xf0
	v_or_b32_e32 v1, v9, v10
	v_and_or_b32 v2, v2, s4, v12
	s_add_u32 s43, s30, 0x2376000
	v_lshl_or_b32 v130, v2, 11, v1
	v_lshrrev_b32_e32 v2, 3, v180
	s_movk_i32 s4, 0x60
	s_addc_u32 s44, s31, 0
	v_and_or_b32 v0, v2, s4, v0
	s_movk_i32 s4, 0x70
	s_ashr_i32 s46, s2, 31
	v_lshl_or_b32 v132, v0, 11, v1
	v_and_or_b32 v0, v2, s4, v12
	s_lshr_b32 s4, s46, 29
	s_add_i32 s4, s2, s4
	s_lshr_b32 s8, s42, 6
	s_ashr_i32 s9, s4, 3
	s_and_b32 s4, s4, -8
	s_lshr_b32 s5, s42, 8
	s_lshl_b32 s45, s8, 10
	s_sub_i32 s4, s2, s4
	s_cmp_lt_i32 s4, 0
	s_movk_i32 s47, 0x221
	s_cselect_b32 s12, s47, 0x220
	s_mul_i32 s4, s12, s4
	s_add_i32 s4, s4, s9
	s_ashr_i32 s9, s4, 31
	s_lshr_b32 s9, s9, 25
	s_add_i32 s9, s4, s9
	s_ashr_i32 s12, s9, 7
	s_and_b32 s9, s9, 0xff80
	s_sub_i32 s9, s4, s9
	s_bfe_i32 s4, s9, 0x80000
	s_bfe_u32 s4, s4, 0x3000c
	s_add_i32 s13, s9, s4
	s_bfe_i32 s4, s13, 0x80000
	s_and_b32 s13, s13, 0xf8
	s_sub_i32 s9, s9, s13
	s_lshl_b32 s12, s12, 3
	s_sext_i32_i16 s4, s4
	s_sext_i32_i8 s9, s9
	s_lshr_b32 s4, s4, 3
	s_add_i32 s12, s12, s9
	s_ashr_i32 s13, s12, 31
	s_bfe_i64 s[16:17], s[4:5], 0x100000
	s_lshl_b64 s[14:15], s[12:13], 19
	s_lshl_b64 s[16:17], s[16:17], 19
	s_add_u32 s38, s30, s16
	s_addc_u32 s39, s31, s17
	s_add_i32 s13, s45, 0
	s_add_i32 m0, s13, 0x10000
	v_lshl_or_b32 v128, v3, 11, v1
	global_load_lds_dwordx4 v132, s[38:39]
	s_add_i32 m0, s13, 0x12000
	s_add_u32 s24, s43, s14
	v_lshl_or_b32 v134, v0, 11, v1
	global_load_lds_dwordx4 v128, s[38:39]
	s_addc_u32 s25, s44, s15
	s_mov_b32 m0, s13
	s_add_i32 s48, s13, 0x2000
	global_load_lds_dwordx4 v134, s[24:25]
	s_mov_b32 m0, s48
	s_add_u32 s14, s38, 0x40000
	global_load_lds_dwordx4 v130, s[24:25]
	s_addc_u32 s15, s39, 0
	s_add_i32 m0, s13, 0x14000
	v_mov_b32_e32 v133, 0
	global_load_lds_dwordx4 v132, s[14:15]
	s_add_i32 m0, s13, 0x16000
	v_mov_b32_e32 v129, v133
	global_load_lds_dwordx4 v128, s[14:15]
	s_add_u32 s14, s24, 0x40000
	s_addc_u32 s15, s25, 0
	s_add_i32 s49, s13, 0x4000
	s_mov_b32 m0, s49
	s_add_i32 s50, s13, 0x6000
	global_load_lds_dwordx4 v134, s[14:15]
	s_mov_b32 m0, s50
	v_mov_b32_e32 v135, v133
	global_load_lds_dwordx4 v130, s[14:15]
	v_mov_b32_e32 v131, v133
	s_mov_b32 s51, 0
	v_lshl_add_u64 v[6:7], s[38:39], 0, v[132:133]
	v_lshl_add_u64 v[4:5], s[38:39], 0, v[128:129]
	v_lshl_add_u64 v[2:3], s[24:25], 0, v[134:135]
	s_cmp_lg_u32 s5, 1
	v_lshl_add_u64 v[0:1], s[24:25], 0, v[130:131]
	s_cbranch_scc1 .LBB0_207
	s_barrier

; #define PG8_WAIT_V(n) asm volatile("s_waitcnt vmcnt(" #n ")" ::: "memory")
; #define PG8_BAR __builtin_amdgcn_s_barrier()
; DI unsigned xb_ld(unsigned* p)              { return __hip_atomic_load(p, __ATOMIC_RELAXED, __HIP_MEMORY_SCOPE_AGENT); }
; template <class Epi>
; DI void gemm_phase(LAS unsigned char* lds, const Gemm g, const StaticOrder& S, const Epi& E) {
;     ...
;     PG8_WAIT_V(0);
;     if (wr == 0) PG8_BAR;
;     PG8_BAR;
; DI void xcd_barrier_complete(unsigned* bar, unsigned x, unsigned& nloc, unsigned& nx) {
;     const unsigned G = gridDim.x * gridDim.y * gridDim.z;
;     unsigned sum, cnt, mine, sp = 0u;
;     for (;;) {
;         sum = 0u; cnt = 0u; mine = 0u;
; #pragma unroll
;         for (unsigned j = 0; j < 16; ++j) { const unsigned c = xb_ld(&bar[XB_XCNT(j)]); sum += c; cnt += (c > 0u) ? 1u : 0u; mine = (j == x) ? c : mine; }
; DI void xcd_barrier(const XcdBarrier& b) {
;     asm volatile("s_waitcnt vmcnt(0)" ::: "memory");
;     __syncthreads();
;     if (threadIdx.x == 0) {
;         unsigned* bar = b.bar;
;         __builtin_amdgcn_s_waitcnt(0);
;         unsigned nloc = b.st[0], nx = b.st[1];
;         if (nloc == 0u) { xcd_barrier_complete(bar, b.x, nloc, nx); b.st[0] = nloc; b.st[1] = nx; }
.LBB0_215:
	s_barrier
.LBB0_216:
.LBB0_221:
	s_or_b64 exec, exec, s[4:5]
	s_cmp_lt_i32 s69, 4
	s_cbranch_scc1 .LBB0_275
	s_waitcnt vmcnt(0)
	s_waitcnt vmcnt(0) lgkmcnt(0)
	s_barrier
	s_and_saveexec_b64 s[4:5], s[10:11]
	s_cbranch_execz .LBB0_274
	s_add_i32 s8, 0, 0x26400
	v_mov_b32_e32 v0, s8
	s_waitcnt vmcnt(0) expcnt(0) lgkmcnt(0)
	ds_read_b32 v2, v0
	s_add_i32 s8, 0, 0x26404
	v_mov_b32_e32 v0, s8
	ds_read_b32 v0, v0
	s_waitcnt lgkmcnt(1)
	v_cmp_ne_u32_e32 vcc, 0, v2
	s_cbranch_vccnz .LBB0_238
	s_load_dwordx2 s[12:13], s[6:7], 0x4
	s_add_u32 s6, s30, 0x34376200
	s_addc_u32 s7, s31, 0
	s_add_u32 s8, s30, 0x34376400
	s_addc_u32 s9, s31, 0
	s_waitcnt lgkmcnt(0)
	s_mul_i32 s3, s12, s3
	s_add_u32 s12, s30, 0x34376500
	s_mul_i32 s3, s3, s13
	s_addc_u32 s13, s31, 0
	s_add_u32 s14, s30, 0x34376600
	s_addc_u32 s15, s31, 0
	s_add_u32 s16, s30, 0x34376700
	s_addc_u32 s17, s31, 0
	s_add_u32 s18, s30, 0x34376800
	s_addc_u32 s19, s31, 0
	s_add_u32 s22, s30, 0x34376900
	s_addc_u32 s23, s31, 0
	s_add_u32 s24, s30, 0x34376a00
	s_addc_u32 s25, s31, 0
	s_add_u32 s38, s30, 0x34376b00
	s_addc_u32 s39, s31, 0
	s_add_u32 s40, s30, 0x34376c00
	s_addc_u32 s41, s31, 0
	s_add_u32 s42, s30, 0x34376d00
	s_addc_u32 s43, s31, 0
	s_add_u32 s44, s30, 0x34376e00
	s_addc_u32 s45, s31, 0
	s_add_u32 s46, s30, 0x34376f00
	s_addc_u32 s47, s31, 0
	s_add_u32 s48, s30, 0x34377000
	s_addc_u32 s49, s31, 0
	s_add_u32 s50, s30, 0x34377100
	s_addc_u32 s51, s31, 0
	s_add_u32 s66, s30, 0x34377200
	s_addc_u32 s67, s31, 0
	s_add_u32 s70, s30, 0x34377300
	s_addc_u32 s71, s31, 0
	s_mov_b32 s78, 1
	v_mov_b32_e32 v16, 0
	s_branch .LBB0_226
